# scan compute waves: y partials of 4 steps written with one ds_write_b128 (16 ds_write_b32 -> 4 per chunk), loader reduces with quad allreduce; loop lgkmcnt waits recomputed
# speedup vs baseline: 1.0186x; 1.0018x over previous
.LBB0_1050:
	s_and_b32 s2, s26, 1
	s_mul_i32 s3, s2, 0x5400
	v_lshlrev_b32_e32 v91, 2, v87
	v_lshl_add_u32 v91, s2, 14, v91
	s_add_i32 s2, s3, 0
	v_add_u32_e32 v0, s2, v85
	v_add_u32_e32 v89, s2, v83
	v_add_u32_e32 v90, s96, v83
	s_add_i32 s96, s96, 0x3000
	s_cmp_eq_u32 s96, 0x1e800
	s_cselect_b32 s96, 0x20200, s96
	s_cmp_eq_u32 s96, 0x23200
	s_cselect_b32 s96, 0x12800, s96
	ds_read_b128 v[14:17], v0 offset:20480
	ds_read_b128 v[10:13], v0 offset:20496
	ds_read_b128 v[6:9], v0 offset:20512
	ds_read_b128 v[2:5], v0 offset:20528
	ds_read_b128 v[62:65], v90
	ds_read_b128 v[46:49], v90 offset:256
	ds_read_b128 v[66:69], v90 offset:4096
	ds_read_b128 v[50:53], v90 offset:4352
	ds_read_b128 v[54:57], v89 offset:16384
	ds_read_b128 v[26:29], v89 offset:16640
	ds_read_b128 v[78:81], v89 offset:4096
	ds_read_b128 v[34:37], v90 offset:512
	ds_read_b128 v[58:61], v89 offset:4352
	ds_read_b128 v[30:33], v89 offset:4608
	ds_read_b128 v[70:73], v90 offset:8192
	ds_read_b128 v[38:41], v90 offset:4608
	ds_read_b128 v[42:45], v90 offset:8448
	ds_read_b128 v[22:25], v90 offset:8704
	ds_read_b128 v[18:21], v89 offset:16896
	s_waitcnt lgkmcnt(12)
	v_pk_mul_f32 v[66:67], v[74:75], v[66:67]
	s_waitcnt lgkmcnt(8)
	v_pk_mul_f32 v[78:79], v[14:15], v[78:79] op_sel_hi:[0,1]
	v_pk_fma_f32 v[66:67], v[76:77], v[68:69], v[66:67]
	v_pk_mul_f32 v[80:81], v[14:15], v[80:81] op_sel_hi:[0,1]
	v_add_f32_e32 v66, v66, v67
	v_pk_fma_f32 v[62:63], v[74:75], v[62:63], v[78:79]
	v_pk_fma_f32 v[64:65], v[76:77], v[64:65], v[80:81]
	v_add_f32_dpp v66, v66, v66 quad_perm:[1,0,3,2] row_mask:0xf bank_mask:0xf bound_ctrl:1
	v_mov_b32_e32 v0, v17
	v_mov_b32_e32 v82, v13
	v_add_f32_dpp v66, v66, v66 quad_perm:[2,3,0,1] row_mask:0xf bank_mask:0xf bound_ctrl:1
	v_mov_b32_e32 v84, v9
	v_mov_b32_e32 v86, v5
	v_add_f32_dpp v66, v66, v66 row_half_mirror row_mask:0xf bank_mask:0xf bound_ctrl:1
	s_add_i32 s26, s26, 1
	s_cmpk_eq_i32 s26, 0x110
	v_add_f32_dpp v66, v66, v66 row_ror:8 row_mask:0xf bank_mask:0xf bound_ctrl:1
	s_waitcnt lgkmcnt(4)
	v_pk_fma_f32 v[62:63], v[70:71], v[66:67], v[62:63] op_sel_hi:[1,0,1] neg_lo:[1,0,0] neg_hi:[1,0,0]
	v_pk_fma_f32 v[64:65], v[72:73], v[66:67], v[64:65] op_sel_hi:[1,0,1] neg_lo:[1,0,0] neg_hi:[1,0,0]
	v_pk_mul_f32 v[50:51], v[50:51], v[62:63]
	v_pk_mul_f32 v[46:47], v[46:47], v[62:63]
	v_pk_fma_f32 v[50:51], v[52:53], v[64:65], v[50:51]
	v_pk_fma_f32 v[66:67], v[14:15], v[58:59], v[46:47] op_sel:[1,0,0]
	v_add_f32_e32 v47, v50, v51
	v_pk_mul_f32 v[48:49], v[48:49], v[64:65]
	v_pk_mul_f32 v[56:57], v[56:57], v[64:65]
	v_add_f32_dpp v68, v47, v47 quad_perm:[1,0,3,2] row_mask:0xf bank_mask:0xf bound_ctrl:1
	v_pk_fma_f32 v[14:15], v[14:15], v[60:61], v[48:49] op_sel:[1,0,0]
	v_pk_fma_f32 v[54:55], v[54:55], v[62:63], v[56:57]
	v_add_f32_dpp v68, v68, v68 quad_perm:[2,3,0,1] row_mask:0xf bank_mask:0xf bound_ctrl:1
	v_add_f32_e32 v92, v54, v55
	v_add_f32_dpp v68, v68, v68 row_half_mirror row_mask:0xf bank_mask:0xf bound_ctrl:1
	ds_read_b128 v[46:49], v90 offset:768
	ds_read_b128 v[50:53], v89 offset:4864
	ds_read_b128 v[54:57], v90 offset:4864
	ds_read_b128 v[58:61], v90 offset:8960
	ds_read_b128 v[62:65], v89 offset:17152
	v_add_f32_dpp v68, v68, v68 row_ror:8 row_mask:0xf bank_mask:0xf bound_ctrl:1
	s_waitcnt lgkmcnt(7)
	v_pk_fma_f32 v[42:43], v[42:43], v[68:69], v[66:67] op_sel_hi:[1,0,1] neg_lo:[1,0,0] neg_hi:[1,0,0]
	v_pk_fma_f32 v[14:15], v[44:45], v[68:69], v[14:15] op_sel_hi:[1,0,1] neg_lo:[1,0,0] neg_hi:[1,0,0]
	v_pk_mul_f32 v[38:39], v[38:39], v[42:43]
	v_pk_mul_f32 v[28:29], v[28:29], v[14:15]
	v_pk_mul_f32 v[36:37], v[36:37], v[14:15]
	v_pk_fma_f32 v[14:15], v[40:41], v[14:15], v[38:39]
	v_pk_mul_f32 v[34:35], v[34:35], v[42:43]
	v_add_f32_e32 v14, v14, v15
	v_pk_fma_f32 v[26:27], v[26:27], v[42:43], v[28:29]
	v_pk_fma_f32 v[42:43], v[16:17], v[30:31], v[34:35] op_sel_hi:[0,1,1]
	v_add_f32_dpp v66, v14, v14 quad_perm:[1,0,3,2] row_mask:0xf bank_mask:0xf bound_ctrl:1
	v_pk_fma_f32 v[44:45], v[16:17], v[32:33], v[36:37] op_sel_hi:[0,1,1]
	v_add_f32_e32 v93, v26, v27
	v_add_f32_dpp v66, v66, v66 quad_perm:[2,3,0,1] row_mask:0xf bank_mask:0xf bound_ctrl:1
	ds_read_b128 v[14:17], v90 offset:1024
	ds_read_b128 v[26:29], v89 offset:5120
	ds_read_b128 v[30:33], v90 offset:5120
	ds_read_b128 v[34:37], v90 offset:9216
	ds_read_b128 v[38:41], v89 offset:17408
	v_add_f32_dpp v66, v66, v66 row_half_mirror row_mask:0xf bank_mask:0xf bound_ctrl:1
	s_nop 1
	v_add_f32_dpp v66, v66, v66 row_ror:8 row_mask:0xf bank_mask:0xf bound_ctrl:1
	s_waitcnt lgkmcnt(11)
	v_pk_fma_f32 v[22:23], v[22:23], v[66:67], v[42:43] op_sel_hi:[1,0,1] neg_lo:[1,0,0] neg_hi:[1,0,0]
	v_pk_fma_f32 v[24:25], v[24:25], v[66:67], v[44:45] op_sel_hi:[1,0,1] neg_lo:[1,0,0] neg_hi:[1,0,0]
	s_waitcnt lgkmcnt(7)
	v_pk_mul_f32 v[42:43], v[54:55], v[22:23]
	v_pk_mul_f32 v[20:21], v[20:21], v[24:25]
	v_pk_mul_f32 v[44:45], v[46:47], v[22:23]
	v_pk_mul_f32 v[46:47], v[48:49], v[24:25]
	v_pk_fma_f32 v[18:19], v[18:19], v[22:23], v[20:21]
	v_pk_fma_f32 v[20:21], v[56:57], v[24:25], v[42:43]
	v_pk_fma_f32 v[54:55], v[0:1], v[50:51], v[44:45] op_sel_hi:[0,1,1]
	v_pk_fma_f32 v[56:57], v[0:1], v[52:53], v[46:47] op_sel_hi:[0,1,1]
	v_add_f32_e32 v94, v18, v19
	v_add_f32_e32 v18, v20, v21
	s_nop 0
	v_add_f32_dpp v0, v18, v18 quad_perm:[1,0,3,2] row_mask:0xf bank_mask:0xf bound_ctrl:1
	ds_read_b128 v[18:21], v90 offset:1280
	ds_read_b128 v[22:25], v89 offset:5376
	v_add_f32_dpp v0, v0, v0 quad_perm:[2,3,0,1] row_mask:0xf bank_mask:0xf bound_ctrl:1
	ds_read_b128 v[42:45], v90 offset:5376
	ds_read_b128 v[46:49], v90 offset:9472
	v_add_f32_dpp v0, v0, v0 row_half_mirror row_mask:0xf bank_mask:0xf bound_ctrl:1
	ds_read_b128 v[50:53], v89 offset:17664
	s_nop 0
	v_add_f32_dpp v0, v0, v0 row_ror:8 row_mask:0xf bank_mask:0xf bound_ctrl:1
	s_waitcnt lgkmcnt(11)
	v_pk_fma_f32 v[54:55], v[58:59], v[0:1], v[54:55] op_sel_hi:[1,0,1] neg_lo:[1,0,0] neg_hi:[1,0,0]
	v_pk_fma_f32 v[56:57], v[60:61], v[0:1], v[56:57] op_sel_hi:[1,0,1] neg_lo:[1,0,0] neg_hi:[1,0,0]
	s_waitcnt lgkmcnt(7)
	v_pk_mul_f32 v[30:31], v[30:31], v[54:55]
	v_pk_mul_f32 v[58:59], v[64:65], v[56:57]
	v_pk_mul_f32 v[14:15], v[14:15], v[54:55]
	v_pk_fma_f32 v[54:55], v[62:63], v[54:55], v[58:59]
	v_pk_fma_f32 v[30:31], v[32:33], v[56:57], v[30:31]
	v_pk_fma_f32 v[62:63], v[10:11], v[26:27], v[14:15] op_sel_hi:[0,1,1]
	v_add_f32_e32 v95, v54, v55
	v_add_f32_e32 v14, v30, v31
	ds_write_b128 v91, v[92:95] offset:43008
	v_pk_mul_f32 v[16:17], v[16:17], v[56:57]
	v_add_f32_dpp v0, v14, v14 quad_perm:[1,0,3,2] row_mask:0xf bank_mask:0xf bound_ctrl:1
	v_pk_fma_f32 v[64:65], v[10:11], v[28:29], v[16:17] op_sel_hi:[0,1,1]
	ds_read_b128 v[14:17], v90 offset:1536
	v_add_f32_dpp v0, v0, v0 quad_perm:[2,3,0,1] row_mask:0xf bank_mask:0xf bound_ctrl:1
	ds_read_b128 v[26:29], v89 offset:5632
	ds_read_b128 v[30:33], v90 offset:5632
	v_add_f32_dpp v0, v0, v0 row_half_mirror row_mask:0xf bank_mask:0xf bound_ctrl:1
	ds_read_b128 v[54:57], v90 offset:9728
	ds_read_b128 v[58:61], v89 offset:17920
	v_add_f32_dpp v0, v0, v0 row_ror:8 row_mask:0xf bank_mask:0xf bound_ctrl:1
	s_waitcnt lgkmcnt(12)
	v_pk_fma_f32 v[34:35], v[34:35], v[0:1], v[62:63] op_sel_hi:[1,0,1] neg_lo:[1,0,0] neg_hi:[1,0,0]
	v_pk_fma_f32 v[36:37], v[36:37], v[0:1], v[64:65] op_sel_hi:[1,0,1] neg_lo:[1,0,0] neg_hi:[1,0,0]
	s_waitcnt lgkmcnt(8)
	v_pk_mul_f32 v[42:43], v[42:43], v[34:35]
	v_pk_mul_f32 v[40:41], v[40:41], v[36:37]
	v_pk_mul_f32 v[18:19], v[18:19], v[34:35]
	v_pk_mul_f32 v[20:21], v[20:21], v[36:37]
	v_pk_fma_f32 v[34:35], v[38:39], v[34:35], v[40:41]
	v_pk_fma_f32 v[36:37], v[44:45], v[36:37], v[42:43]
	v_pk_fma_f32 v[62:63], v[10:11], v[22:23], v[18:19] op_sel:[1,0,0]
	v_add_f32_e32 v96, v34, v35
	v_add_f32_e32 v18, v36, v37
	v_pk_fma_f32 v[10:11], v[10:11], v[24:25], v[20:21] op_sel:[1,0,0]
	v_add_f32_dpp v0, v18, v18 quad_perm:[1,0,3,2] row_mask:0xf bank_mask:0xf bound_ctrl:1
	ds_read_b128 v[18:21], v90 offset:1792
	ds_read_b128 v[22:25], v89 offset:5888
	v_add_f32_dpp v0, v0, v0 quad_perm:[2,3,0,1] row_mask:0xf bank_mask:0xf bound_ctrl:1
	ds_read_b128 v[34:37], v90 offset:5888
	ds_read_b128 v[38:41], v90 offset:9984
	v_add_f32_dpp v0, v0, v0 row_half_mirror row_mask:0xf bank_mask:0xf bound_ctrl:1
	ds_read_b128 v[42:45], v89 offset:18176
	s_nop 0
	v_add_f32_dpp v0, v0, v0 row_ror:8 row_mask:0xf bank_mask:0xf bound_ctrl:1
	s_waitcnt lgkmcnt(12)
	v_pk_fma_f32 v[46:47], v[46:47], v[0:1], v[62:63] op_sel_hi:[1,0,1] neg_lo:[1,0,0] neg_hi:[1,0,0]
	v_pk_fma_f32 v[10:11], v[48:49], v[0:1], v[10:11] op_sel_hi:[1,0,1] neg_lo:[1,0,0] neg_hi:[1,0,0]
	s_waitcnt lgkmcnt(7)
	v_pk_mul_f32 v[30:31], v[30:31], v[46:47]
	v_pk_mul_f32 v[48:49], v[52:53], v[10:11]
	v_pk_mul_f32 v[14:15], v[14:15], v[46:47]
	v_pk_mul_f32 v[16:17], v[16:17], v[10:11]
	v_pk_fma_f32 v[46:47], v[50:51], v[46:47], v[48:49]
	v_pk_fma_f32 v[10:11], v[32:33], v[10:11], v[30:31]
	v_add_f32_e32 v97, v46, v47
	v_add_f32_e32 v10, v10, v11
	v_pk_fma_f32 v[50:51], v[12:13], v[26:27], v[14:15] op_sel_hi:[0,1,1]
	v_add_f32_dpp v0, v10, v10 quad_perm:[1,0,3,2] row_mask:0xf bank_mask:0xf bound_ctrl:1
	v_pk_fma_f32 v[52:53], v[12:13], v[28:29], v[16:17] op_sel_hi:[0,1,1]
	ds_read_b128 v[10:13], v90 offset:2048
	v_add_f32_dpp v0, v0, v0 quad_perm:[2,3,0,1] row_mask:0xf bank_mask:0xf bound_ctrl:1
	ds_read_b128 v[14:17], v89 offset:6144
	ds_read_b128 v[26:29], v90 offset:6144
	v_add_f32_dpp v0, v0, v0 row_half_mirror row_mask:0xf bank_mask:0xf bound_ctrl:1
	ds_read_b128 v[30:33], v90 offset:10240
	ds_read_b128 v[46:49], v89 offset:18432
	v_add_f32_dpp v0, v0, v0 row_ror:8 row_mask:0xf bank_mask:0xf bound_ctrl:1
	s_waitcnt lgkmcnt(11)
	v_pk_fma_f32 v[50:51], v[54:55], v[0:1], v[50:51] op_sel_hi:[1,0,1] neg_lo:[1,0,0] neg_hi:[1,0,0]
	v_pk_fma_f32 v[52:53], v[56:57], v[0:1], v[52:53] op_sel_hi:[1,0,1] neg_lo:[1,0,0] neg_hi:[1,0,0]
	s_waitcnt lgkmcnt(7)
	v_pk_mul_f32 v[34:35], v[34:35], v[50:51]
	v_pk_mul_f32 v[54:55], v[60:61], v[52:53]
	v_pk_mul_f32 v[18:19], v[18:19], v[50:51]
	v_pk_fma_f32 v[50:51], v[58:59], v[50:51], v[54:55]
	v_pk_fma_f32 v[34:35], v[36:37], v[52:53], v[34:35]
	v_pk_fma_f32 v[58:59], v[82:83], v[22:23], v[18:19] op_sel_hi:[0,1,1]
	v_add_f32_e32 v98, v50, v51
	v_add_f32_e32 v18, v34, v35
	v_pk_mul_f32 v[20:21], v[20:21], v[52:53]
	v_add_f32_dpp v0, v18, v18 quad_perm:[1,0,3,2] row_mask:0xf bank_mask:0xf bound_ctrl:1
	v_pk_fma_f32 v[60:61], v[82:83], v[24:25], v[20:21] op_sel_hi:[0,1,1]
	ds_read_b128 v[18:21], v90 offset:2304
	v_add_f32_dpp v0, v0, v0 quad_perm:[2,3,0,1] row_mask:0xf bank_mask:0xf bound_ctrl:1
	ds_read_b128 v[22:25], v89 offset:6400
	ds_read_b128 v[34:37], v90 offset:6400
	v_add_f32_dpp v0, v0, v0 row_half_mirror row_mask:0xf bank_mask:0xf bound_ctrl:1
	ds_read_b128 v[50:53], v90 offset:10496
	ds_read_b128 v[54:57], v89 offset:18688
	v_add_f32_dpp v0, v0, v0 row_ror:8 row_mask:0xf bank_mask:0xf bound_ctrl:1
	s_waitcnt lgkmcnt(11)
	v_pk_fma_f32 v[38:39], v[38:39], v[0:1], v[58:59] op_sel_hi:[1,0,1] neg_lo:[1,0,0] neg_hi:[1,0,0]
	v_pk_fma_f32 v[40:41], v[40:41], v[0:1], v[60:61] op_sel_hi:[1,0,1] neg_lo:[1,0,0] neg_hi:[1,0,0]
	s_waitcnt lgkmcnt(7)
	v_pk_mul_f32 v[26:27], v[26:27], v[38:39]
	v_pk_mul_f32 v[44:45], v[44:45], v[40:41]
	v_pk_mul_f32 v[10:11], v[10:11], v[38:39]
	v_pk_fma_f32 v[38:39], v[42:43], v[38:39], v[44:45]
	v_pk_fma_f32 v[26:27], v[28:29], v[40:41], v[26:27]
	v_pk_fma_f32 v[58:59], v[6:7], v[14:15], v[10:11] op_sel_hi:[0,1,1]
	v_add_f32_e32 v99, v38, v39
	v_add_f32_e32 v10, v26, v27
	ds_write_b128 v91, v[96:99] offset:47104
	v_pk_mul_f32 v[12:13], v[12:13], v[40:41]
	v_add_f32_dpp v0, v10, v10 quad_perm:[1,0,3,2] row_mask:0xf bank_mask:0xf bound_ctrl:1
	v_pk_fma_f32 v[60:61], v[6:7], v[16:17], v[12:13] op_sel_hi:[0,1,1]
	ds_read_b128 v[10:13], v90 offset:2560
	v_add_f32_dpp v0, v0, v0 quad_perm:[2,3,0,1] row_mask:0xf bank_mask:0xf bound_ctrl:1
	ds_read_b128 v[14:17], v89 offset:6656
	ds_read_b128 v[26:29], v90 offset:6656
	v_add_f32_dpp v0, v0, v0 row_half_mirror row_mask:0xf bank_mask:0xf bound_ctrl:1
	ds_read_b128 v[38:41], v90 offset:10752
	ds_read_b128 v[42:45], v89 offset:18944
	v_add_f32_dpp v0, v0, v0 row_ror:8 row_mask:0xf bank_mask:0xf bound_ctrl:1
	s_waitcnt lgkmcnt(12)
	v_pk_fma_f32 v[30:31], v[30:31], v[0:1], v[58:59] op_sel_hi:[1,0,1] neg_lo:[1,0,0] neg_hi:[1,0,0]
	v_pk_fma_f32 v[32:33], v[32:33], v[0:1], v[60:61] op_sel_hi:[1,0,1] neg_lo:[1,0,0] neg_hi:[1,0,0]
	s_waitcnt lgkmcnt(8)
	v_pk_mul_f32 v[34:35], v[34:35], v[30:31]
	v_pk_mul_f32 v[48:49], v[48:49], v[32:33]
	v_pk_mul_f32 v[18:19], v[18:19], v[30:31]
	v_pk_mul_f32 v[20:21], v[20:21], v[32:33]
	v_pk_fma_f32 v[30:31], v[46:47], v[30:31], v[48:49]
	v_pk_fma_f32 v[32:33], v[36:37], v[32:33], v[34:35]
	v_pk_fma_f32 v[58:59], v[6:7], v[22:23], v[18:19] op_sel:[1,0,0]
	v_add_f32_e32 v92, v30, v31
	v_add_f32_e32 v18, v32, v33
	v_pk_fma_f32 v[6:7], v[6:7], v[24:25], v[20:21] op_sel:[1,0,0]
	v_add_f32_dpp v0, v18, v18 quad_perm:[1,0,3,2] row_mask:0xf bank_mask:0xf bound_ctrl:1
	ds_read_b128 v[18:21], v90 offset:2816
	ds_read_b128 v[22:25], v89 offset:6912
	v_add_f32_dpp v0, v0, v0 quad_perm:[2,3,0,1] row_mask:0xf bank_mask:0xf bound_ctrl:1
	ds_read_b128 v[30:33], v90 offset:6912
	ds_read_b128 v[34:37], v90 offset:11008
	v_add_f32_dpp v0, v0, v0 row_half_mirror row_mask:0xf bank_mask:0xf bound_ctrl:1
	ds_read_b128 v[46:49], v89 offset:19200
	s_nop 0
	v_add_f32_dpp v0, v0, v0 row_ror:8 row_mask:0xf bank_mask:0xf bound_ctrl:1
	s_waitcnt lgkmcnt(12)
	v_pk_fma_f32 v[50:51], v[50:51], v[0:1], v[58:59] op_sel_hi:[1,0,1] neg_lo:[1,0,0] neg_hi:[1,0,0]
	v_pk_fma_f32 v[6:7], v[52:53], v[0:1], v[6:7] op_sel_hi:[1,0,1] neg_lo:[1,0,0] neg_hi:[1,0,0]
	s_waitcnt lgkmcnt(7)
	v_pk_mul_f32 v[26:27], v[26:27], v[50:51]
	v_pk_mul_f32 v[52:53], v[56:57], v[6:7]
	v_pk_mul_f32 v[10:11], v[10:11], v[50:51]
	v_pk_mul_f32 v[12:13], v[12:13], v[6:7]
	v_pk_fma_f32 v[50:51], v[54:55], v[50:51], v[52:53]
	v_pk_fma_f32 v[6:7], v[28:29], v[6:7], v[26:27]
	v_add_f32_e32 v93, v50, v51
	v_add_f32_e32 v6, v6, v7
	v_pk_fma_f32 v[54:55], v[8:9], v[14:15], v[10:11] op_sel_hi:[0,1,1]
	v_add_f32_dpp v0, v6, v6 quad_perm:[1,0,3,2] row_mask:0xf bank_mask:0xf bound_ctrl:1
	v_pk_fma_f32 v[56:57], v[8:9], v[16:17], v[12:13] op_sel_hi:[0,1,1]
	ds_read_b128 v[6:9], v90 offset:3072
	v_add_f32_dpp v0, v0, v0 quad_perm:[2,3,0,1] row_mask:0xf bank_mask:0xf bound_ctrl:1
	ds_read_b128 v[10:13], v89 offset:7168
	ds_read_b128 v[14:17], v90 offset:7168
	v_add_f32_dpp v0, v0, v0 row_half_mirror row_mask:0xf bank_mask:0xf bound_ctrl:1
	ds_read_b128 v[26:29], v90 offset:11264
	ds_read_b128 v[50:53], v89 offset:19456
	v_add_f32_dpp v0, v0, v0 row_ror:8 row_mask:0xf bank_mask:0xf bound_ctrl:1
	s_waitcnt lgkmcnt(11)
	v_pk_fma_f32 v[38:39], v[38:39], v[0:1], v[54:55] op_sel_hi:[1,0,1] neg_lo:[1,0,0] neg_hi:[1,0,0]
	v_pk_fma_f32 v[40:41], v[40:41], v[0:1], v[56:57] op_sel_hi:[1,0,1] neg_lo:[1,0,0] neg_hi:[1,0,0]
	s_waitcnt lgkmcnt(7)
	v_pk_mul_f32 v[30:31], v[30:31], v[38:39]
	v_pk_mul_f32 v[44:45], v[44:45], v[40:41]
	v_pk_mul_f32 v[18:19], v[18:19], v[38:39]
	v_pk_fma_f32 v[38:39], v[42:43], v[38:39], v[44:45]
	v_pk_fma_f32 v[30:31], v[32:33], v[40:41], v[30:31]
	v_pk_fma_f32 v[54:55], v[84:85], v[22:23], v[18:19] op_sel_hi:[0,1,1]
	v_add_f32_e32 v94, v38, v39
	v_add_f32_e32 v18, v30, v31
	v_pk_mul_f32 v[20:21], v[20:21], v[40:41]
	v_add_f32_dpp v0, v18, v18 quad_perm:[1,0,3,2] row_mask:0xf bank_mask:0xf bound_ctrl:1
	v_pk_fma_f32 v[56:57], v[84:85], v[24:25], v[20:21] op_sel_hi:[0,1,1]
	ds_read_b128 v[18:21], v90 offset:3328
	v_add_f32_dpp v0, v0, v0 quad_perm:[2,3,0,1] row_mask:0xf bank_mask:0xf bound_ctrl:1
	ds_read_b128 v[22:25], v89 offset:7424
	ds_read_b128 v[30:33], v90 offset:7424
	v_add_f32_dpp v0, v0, v0 row_half_mirror row_mask:0xf bank_mask:0xf bound_ctrl:1
	ds_read_b128 v[38:41], v90 offset:11520
	ds_read_b128 v[42:45], v89 offset:19712
	v_add_f32_dpp v0, v0, v0 row_ror:8 row_mask:0xf bank_mask:0xf bound_ctrl:1
	s_waitcnt lgkmcnt(11)
	v_pk_fma_f32 v[34:35], v[34:35], v[0:1], v[54:55] op_sel_hi:[1,0,1] neg_lo:[1,0,0] neg_hi:[1,0,0]
	v_pk_fma_f32 v[36:37], v[36:37], v[0:1], v[56:57] op_sel_hi:[1,0,1] neg_lo:[1,0,0] neg_hi:[1,0,0]
	s_waitcnt lgkmcnt(7)
	v_pk_mul_f32 v[14:15], v[14:15], v[34:35]
	v_pk_mul_f32 v[48:49], v[48:49], v[36:37]
	v_pk_mul_f32 v[6:7], v[6:7], v[34:35]
	v_pk_fma_f32 v[34:35], v[46:47], v[34:35], v[48:49]
	v_pk_fma_f32 v[14:15], v[16:17], v[36:37], v[14:15]
	v_pk_fma_f32 v[54:55], v[2:3], v[10:11], v[6:7] op_sel_hi:[0,1,1]
	v_add_f32_e32 v95, v34, v35
	v_add_f32_e32 v6, v14, v15
	ds_write_b128 v91, v[92:95] offset:51200
	v_pk_mul_f32 v[8:9], v[8:9], v[36:37]
	v_add_f32_dpp v0, v6, v6 quad_perm:[1,0,3,2] row_mask:0xf bank_mask:0xf bound_ctrl:1
	v_pk_fma_f32 v[56:57], v[2:3], v[12:13], v[8:9] op_sel_hi:[0,1,1]
	ds_read_b128 v[6:9], v90 offset:3584
	v_add_f32_dpp v0, v0, v0 quad_perm:[2,3,0,1] row_mask:0xf bank_mask:0xf bound_ctrl:1
	ds_read_b128 v[10:13], v89 offset:7680
	ds_read_b128 v[14:17], v90 offset:7680
	v_add_f32_dpp v0, v0, v0 row_half_mirror row_mask:0xf bank_mask:0xf bound_ctrl:1
	ds_read_b128 v[34:37], v90 offset:11776
	ds_read_b128 v[46:49], v89 offset:19968
	v_add_f32_dpp v0, v0, v0 row_ror:8 row_mask:0xf bank_mask:0xf bound_ctrl:1
	s_waitcnt lgkmcnt(12)
	v_pk_fma_f32 v[26:27], v[26:27], v[0:1], v[54:55] op_sel_hi:[1,0,1] neg_lo:[1,0,0] neg_hi:[1,0,0]
	v_pk_fma_f32 v[28:29], v[28:29], v[0:1], v[56:57] op_sel_hi:[1,0,1] neg_lo:[1,0,0] neg_hi:[1,0,0]
	s_waitcnt lgkmcnt(8)
	v_pk_mul_f32 v[30:31], v[30:31], v[26:27]
	v_pk_mul_f32 v[52:53], v[52:53], v[28:29]
	v_pk_mul_f32 v[18:19], v[18:19], v[26:27]
	v_pk_mul_f32 v[20:21], v[20:21], v[28:29]
	v_pk_fma_f32 v[26:27], v[50:51], v[26:27], v[52:53]
	v_pk_fma_f32 v[28:29], v[32:33], v[28:29], v[30:31]
	v_pk_fma_f32 v[54:55], v[2:3], v[22:23], v[18:19] op_sel:[1,0,0]
	v_add_f32_e32 v96, v26, v27
	v_add_f32_e32 v18, v28, v29
	v_pk_fma_f32 v[2:3], v[2:3], v[24:25], v[20:21] op_sel:[1,0,0]
	v_add_f32_dpp v0, v18, v18 quad_perm:[1,0,3,2] row_mask:0xf bank_mask:0xf bound_ctrl:1
	ds_read_b128 v[18:21], v90 offset:3840
	ds_read_b128 v[22:25], v89 offset:7936
	v_add_f32_dpp v0, v0, v0 quad_perm:[2,3,0,1] row_mask:0xf bank_mask:0xf bound_ctrl:1
	ds_read_b128 v[26:29], v90 offset:7936
	ds_read_b128 v[30:33], v90 offset:12032
	v_add_f32_dpp v0, v0, v0 row_half_mirror row_mask:0xf bank_mask:0xf bound_ctrl:1
	ds_read_b128 v[50:53], v89 offset:20224
	s_nop 0
	v_add_f32_dpp v0, v0, v0 row_ror:8 row_mask:0xf bank_mask:0xf bound_ctrl:1
	s_waitcnt lgkmcnt(12)
	v_pk_fma_f32 v[38:39], v[38:39], v[0:1], v[54:55] op_sel_hi:[1,0,1] neg_lo:[1,0,0] neg_hi:[1,0,0]
	v_pk_fma_f32 v[2:3], v[40:41], v[0:1], v[2:3] op_sel_hi:[1,0,1] neg_lo:[1,0,0] neg_hi:[1,0,0]
	s_waitcnt lgkmcnt(7)
	v_pk_mul_f32 v[14:15], v[14:15], v[38:39]
	v_pk_mul_f32 v[40:41], v[44:45], v[2:3]
	v_pk_mul_f32 v[8:9], v[8:9], v[2:3]
	v_pk_fma_f32 v[2:3], v[16:17], v[2:3], v[14:15]
	v_pk_mul_f32 v[6:7], v[6:7], v[38:39]
	v_add_f32_e32 v0, v2, v3
	v_pk_fma_f32 v[6:7], v[4:5], v[10:11], v[6:7] op_sel_hi:[0,1,1]
	v_pk_fma_f32 v[4:5], v[4:5], v[12:13], v[8:9] op_sel_hi:[0,1,1]
	v_add_f32_dpp v0, v0, v0 quad_perm:[1,0,3,2] row_mask:0xf bank_mask:0xf bound_ctrl:1
	v_pk_fma_f32 v[38:39], v[42:43], v[38:39], v[40:41]
	s_nop 0
	v_add_f32_dpp v0, v0, v0 quad_perm:[2,3,0,1] row_mask:0xf bank_mask:0xf bound_ctrl:1
	v_add_f32_e32 v97, v38, v39
	s_nop 0
	v_add_f32_dpp v0, v0, v0 row_half_mirror row_mask:0xf bank_mask:0xf bound_ctrl:1
	s_nop 1
	v_add_f32_dpp v0, v0, v0 row_ror:8 row_mask:0xf bank_mask:0xf bound_ctrl:1
	s_waitcnt lgkmcnt(6)
	v_pk_fma_f32 v[2:3], v[34:35], v[0:1], v[6:7] op_sel_hi:[1,0,1] neg_lo:[1,0,0] neg_hi:[1,0,0]
	v_pk_fma_f32 v[4:5], v[36:37], v[0:1], v[4:5] op_sel_hi:[1,0,1] neg_lo:[1,0,0] neg_hi:[1,0,0]
	s_waitcnt lgkmcnt(2)
	v_pk_mul_f32 v[8:9], v[26:27], v[2:3]
	v_pk_mul_f32 v[6:7], v[48:49], v[4:5]
	v_pk_mul_f32 v[10:11], v[18:19], v[2:3]
	v_pk_mul_f32 v[12:13], v[20:21], v[4:5]
	v_pk_fma_f32 v[2:3], v[46:47], v[2:3], v[6:7]
	v_pk_fma_f32 v[4:5], v[28:29], v[4:5], v[8:9]
	v_add_f32_e32 v98, v2, v3
	v_add_f32_e32 v2, v4, v5
	v_pk_fma_f32 v[8:9], v[86:87], v[24:25], v[12:13] op_sel_hi:[0,1,1]
	v_add_f32_dpp v0, v2, v2 quad_perm:[1,0,3,2] row_mask:0xf bank_mask:0xf bound_ctrl:1
	v_pk_fma_f32 v[6:7], v[86:87], v[22:23], v[10:11] op_sel_hi:[0,1,1]
	s_nop 0
	v_add_f32_dpp v0, v0, v0 quad_perm:[2,3,0,1] row_mask:0xf bank_mask:0xf bound_ctrl:1
	s_nop 1
	v_add_f32_dpp v0, v0, v0 row_half_mirror row_mask:0xf bank_mask:0xf bound_ctrl:1
	s_nop 1
	v_add_f32_dpp v0, v0, v0 row_ror:8 row_mask:0xf bank_mask:0xf bound_ctrl:1
	s_waitcnt lgkmcnt(1)
	v_pk_fma_f32 v[76:77], v[32:33], v[0:1], v[8:9] op_sel_hi:[1,0,1] neg_lo:[1,0,0] neg_hi:[1,0,0]
	v_pk_fma_f32 v[74:75], v[30:31], v[0:1], v[6:7] op_sel_hi:[1,0,1] neg_lo:[1,0,0] neg_hi:[1,0,0]
	s_waitcnt lgkmcnt(0)
	v_pk_mul_f32 v[2:3], v[52:53], v[76:77]
	s_nop 0
	v_pk_fma_f32 v[2:3], v[50:51], v[74:75], v[2:3]
	s_nop 0
	v_add_f32_e32 v99, v2, v3
	ds_write_b128 v91, v[96:99] offset:55296
	s_waitcnt lgkmcnt(0)
	s_barrier
	s_cbranch_scc0 .LBB0_1050
	s_setprio 0
.LBB0_1051:
	s_andn2_saveexec_b64 s[14:15], s[24:25]
	s_cbranch_execz .LBB0_1278
	v_and_b32_e32 v125, 3, v232
	v_and_b32_e32 v123, 0xc0, v232
	v_lshlrev_b32_e32 v123, 4, v123
	v_mov_b32_e32 v122, 0x20200
	s_lshl_b32 s2, s30, 2
	s_and_b32 s33, s2, 28
	s_ashr_i32 s2, s30, 5
	s_add_i32 s33, s33, s2
	s_ashr_i32 s3, s33, 3
	s_and_b32 s37, s2, 1
	s_cmp_eq_u32 s37, 0
	s_cselect_b64 s[16:17], -1, 0
	s_cmp_eq_u32 s37, 1
	s_cselect_b64 s[34:35], -1, 0
	s_lshl_b32 s24, s3, 12
	s_lshl_b32 s61, s3, 8
	v_add_u32_e32 v39, 0xffffff00, v4
	s_movk_i32 s2, 0xfff
	s_add_i32 s31, s24, 0x10ff
	s_add_i32 s43, s61, 0x40ff
	v_lshrrev_b32_e32 v55, 4, v39
	v_cmp_lt_u32_e64 s[44:45], s2, v39
	s_mov_b64 s[26:27], -1
	s_and_b64 vcc, exec, s[34:35]
	s_cbranch_vccz .LBB0_1058
	s_and_saveexec_b64 s[26:27], s[44:45]
	s_xor_b64 s[26:27], exec, s[26:27]
	v_sub_u32_e32 v2, s31, v55
	s_andn2_saveexec_b64 s[26:27], s[26:27]
	v_sub_u32_e32 v2, s43, v55
	s_or_b64 exec, exec, s[26:27]
	s_mov_b64 s[26:27], 0

.LBB0_1102:
	v_ashrrev_i32_e32 v45, 31, v44
	v_lshlrev_b64 v[26:27], 1, v[44:45]
	v_or_b32_e32 v26, s37, v26
	v_readlane_b32 s2, v252, 0
	v_readlane_b32 s4, v252, 6
	v_or_b32_e32 v43, s61, v90
	v_sub_u32_e32 v46, s27, v90
	v_lshlrev_b64 v[30:31], 10, v[26:27]
	v_readlane_b32 s3, v252, 1
	v_lshlrev_b64 v[26:27], 9, v[26:27]
	v_readlane_b32 s5, v252, 7
	v_cndmask_b32_e64 v46, v46, v43, s[16:17]
	v_lshl_add_u64 v[28:29], s[2:3], 0, v[30:31]
	v_lshl_add_u64 v[26:27], s[4:5], 0, v[26:27]
	v_mov_b32_e32 v41, v1
	v_ashrrev_i32_e32 v47, 31, v46
	v_readlane_b32 s8, v252, 10
	v_lshl_add_u64 v[28:29], v[28:29], 0, v[0:1]
	v_lshl_add_u64 v[32:33], v[26:27], 0, v[40:41]
	v_readlane_b32 s10, v252, 20
	v_readlane_b32 s12, v252, 22
	v_readlane_b32 s6, v252, 8
	v_lshlrev_b64 v[46:47], 9, v[46:47]
	v_readlane_b32 s9, v252, 11
	v_add_u32_e32 v124, 0x1b800, v123
	s_nop 0
	v_readfirstlane_b32 s98, v124
	s_mov_b32 m0, s98
	s_nop 0
	global_load_lds_dwordx4 v[28:29], off
	s_nop 0
	global_load_dwordx2 v[82:83], v[32:33], off
	v_lshlrev_b64 v[32:33], 10, v[44:45]
	v_readlane_b32 s11, v252, 21
	v_readlane_b32 s13, v252, 23
	v_lshlrev_b64 v[44:45], 9, v[44:45]
	v_readlane_b32 s7, v252, 9
	v_lshl_add_u64 v[46:47], s[8:9], 0, v[46:47]
	s_mov_b32 s27, s21
	v_lshl_add_u64 v[32:33], s[10:11], 0, v[32:33]
	v_lshl_add_u64 v[30:31], s[12:13], 0, v[30:31]
	v_lshl_add_u64 v[44:45], s[6:7], 0, v[44:45]
	v_lshl_add_u64 v[46:47], v[46:47], 0, s[26:27]
	s_mov_b32 s49, s21
	v_lshl_add_u64 v[32:33], v[32:33], 0, v[0:1]
	v_lshl_add_u64 v[34:35], v[30:31], 0, v[0:1]
	v_lshl_add_u64 v[44:45], v[44:45], 0, v[40:41]
	v_lshl_add_u64 v[46:47], v[46:47], 0, s[48:49]
	v_mov_b32_e32 v43, v1
	v_add_u32_e32 v124, 0x1c800, v123
	s_nop 0
	v_readfirstlane_b32 s98, v124
	s_mov_b32 m0, s98
	s_nop 0
	global_load_lds_dwordx4 v[32:33], off
	s_nop 0
	v_add_u32_e32 v124, 0x1d800, v123
	s_nop 0
	v_readfirstlane_b32 s98, v124
	s_mov_b32 m0, s98
	s_nop 0
	global_load_lds_dwordx4 v[34:35], off
	v_lshl_add_u64 v[46:47], v[46:47], 0, v[42:43]
	global_load_dwordx2 v[84:85], v[44:45], off
	global_load_dwordx2 v[86:87], v[46:47], off
	s_lshl_b32 s20, s37, 10
	v_lshl_add_u64 v[60:61], s[2:3], 0, v[0:1]
	s_add_u32 s2, s8, s26
	s_addc_u32 s3, s9, 0
	s_add_u32 s26, s2, s48
	s_addc_u32 s27, s3, 0
	v_readlane_b32 s2, v252, 14
	v_readlane_b32 s3, v252, 15
	s_add_u32 s2, s2, s20
	s_addc_u32 s3, s3, 0
	s_lshl_b32 s48, s60, 2
	s_add_u32 s2, s2, s48
	s_addc_u32 s3, s3, 0
	s_lshl_b32 s50, s33, 2
	s_waitcnt lgkmcnt(0)
	s_barrier
	v_lshl_add_u64 v[70:71], s[26:27], 0, v[42:43]
	s_add_u32 s26, s2, s50
	v_lshl_add_u64 v[64:65], s[10:11], 0, v[0:1]
	v_lshl_add_u64 v[66:67], s[12:13], 0, v[0:1]
	v_lshlrev_b32_e32 v0, 6, v39
	v_lshrrev_b32_e32 v94, 2, v39
	s_addc_u32 s27, s3, 0
	v_mov_b32_e32 v39, v1
	v_lshl_add_u64 v[62:63], s[4:5], 0, v[40:41]
	v_lshl_add_u64 v[68:69], s[6:7], 0, v[40:41]
	v_and_b32_e32 v93, 0xc0, v0
	v_add_u32_e32 v0, 0, v0
	v_lshl_add_u64 v[72:73], s[26:27], 0, v[38:39]
	s_sub_i32 s98, 1, s37
	s_sub_i32 s98, s98, s37
	s_ashr_i32 s99, s98, 31
	v_mov_b32_e32 v112, s98
	v_mov_b32_e32 v113, s99
	s_cmp_eq_u32 s37, 0
	s_cselect_b32 s98, 64, 0xbf
	s_add_i32 s98, s98, s25
	v_mov_b32_e32 v110, s98
	v_mad_i32_i24 v111, v55, v112, v110
	v_and_b32_e32 v108, 63, v232
	v_lshrrev_b32_e32 v108, 2, v108
	v_mad_i32_i24 v109, v108, v112, v110
	v_lshl_or_b32 v108, v111, 1, s37
	s_movk_i32 s98, 0x400
	s_movk_i32 s99, 0x200
	v_mad_u64_u32 v[96:97], vcc, v108, s98, v[60:61]
	v_mad_u64_u32 v[98:99], vcc, v108, s99, v[62:63]
	v_mad_u64_u32 v[100:101], vcc, v111, s98, v[64:65]
	v_mad_u64_u32 v[102:103], vcc, v108, s98, v[66:67]
	v_mad_u64_u32 v[104:105], vcc, v111, s99, v[68:69]
	v_mad_u64_u32 v[106:107], vcc, v109, s99, v[70:71]
	s_cmp_eq_u32 s37, 0
	s_cselect_b32 s98, 0, 0xff
	s_add_i32 s98, s98, s25
	v_mov_b32_e32 v110, s98
	v_mad_i32_i24 v111, v55, v112, v110
	s_movk_i32 s98, 0x800
	v_mad_u64_u32 v[108:109], vcc, v111, s98, v[72:73]
	v_and_b32_e32 v126, 0xff, v232
	v_lshrrev_b32_e32 v127, 6, v126
	v_and_b32_e32 v128, 3, v126
	v_lshl_add_u32 v127, v127, 2, v128
	v_lshrrev_b32_e32 v128, 4, v126
	v_sub_u32_e32 v127, v127, v128
	v_mul_i32_i24_e32 v127, v127, v112
	v_lshlrev_b32_e32 v127, 11, v127
	v_bfe_u32 v128, v126, 2, 4
	v_and_b32_e32 v129, 15, v126
	v_sub_u32_e32 v128, v128, v129
	v_lshl_add_u32 v128, v128, 2, v127
	v_ashrrev_i32_e32 v129, 31, v128
	v_lshl_add_u64 v[108:109], v[128:129], 0, v[108:109]
	s_sub_i32 s98, s24, s25
	s_movk_i32 s99, 0x1000
	s_cmp_eq_u32 s37, 0
	s_cselect_b32 s99, 0xffffff00, s99
	s_add_i32 s98, s98, s99
	s_lshl_b32 s98, s98, 9
	s_ashr_i32 s99, s98, 31
	v_mov_b32_e32 v120, s98
	v_mov_b32_e32 v121, s99
	s_lshl_b32 s98, s98, 1
	v_mov_b32_e32 v118, s98
	v_mov_b32_e32 v119, s99
	s_lshl_b32 s98, s98, 1
	v_mov_b32_e32 v110, s98
	v_mov_b32_e32 v111, s99
	v_lshlrev_b32_e32 v112, 15, v112
	v_ashrrev_i32_e32 v114, 1, v112
	v_mov_b32_e32 v115, v113
	v_ashrrev_i32_e32 v116, 2, v112
	v_mov_b32_e32 v117, v113
	s_mov_b32 s49, 0
	s_mov_b32 s51, 0
	s_branch .LBB0_1106

.LBB0_1104:
	s_waitcnt lgkmcnt(2)
	v_pk_add_f32 v[48:49], v[48:49], v[52:53]
	v_pk_add_f32 v[46:47], v[46:47], v[50:51]
	s_waitcnt lgkmcnt(0)
	v_pk_add_f32 v[40:41], v[40:41], v[44:45]
	v_pk_add_f32 v[38:39], v[38:39], v[42:43]
	v_pk_add_f32 v[40:41], v[48:49], v[40:41]
	v_pk_add_f32 v[38:39], v[46:47], v[38:39]
	s_nop 1
	v_add_f32_dpp v38, v38, v38 quad_perm:[1,0,3,2] row_mask:0xf bank_mask:0xf bound_ctrl:1
	v_add_f32_dpp v39, v39, v39 quad_perm:[1,0,3,2] row_mask:0xf bank_mask:0xf bound_ctrl:1
	v_add_f32_dpp v40, v40, v40 quad_perm:[1,0,3,2] row_mask:0xf bank_mask:0xf bound_ctrl:1
	v_add_f32_dpp v41, v41, v41 quad_perm:[1,0,3,2] row_mask:0xf bank_mask:0xf bound_ctrl:1
	v_add_f32_dpp v38, v38, v38 quad_perm:[2,3,0,1] row_mask:0xf bank_mask:0xf bound_ctrl:1
	v_add_f32_dpp v39, v39, v39 quad_perm:[2,3,0,1] row_mask:0xf bank_mask:0xf bound_ctrl:1
	v_add_f32_dpp v40, v40, v40 quad_perm:[2,3,0,1] row_mask:0xf bank_mask:0xf bound_ctrl:1
	v_add_f32_dpp v41, v41, v41 quad_perm:[2,3,0,1] row_mask:0xf bank_mask:0xf bound_ctrl:1
	v_cmp_eq_u32_e64 s[2:3], 1, v125
	s_nop 1
	v_cndmask_b32_e64 v38, v38, v39, s[2:3]
	v_cmp_eq_u32_e64 s[2:3], 2, v125
	s_nop 1
	v_cndmask_b32_e64 v38, v38, v40, s[2:3]
	v_cmp_eq_u32_e64 s[2:3], 3, v125
	s_nop 1
	v_cndmask_b32_e64 v40, v38, v41, s[2:3]
	s_cmp_lg_u32 s49, 15
	s_cbranch_scc1 .Lscan_y_nofix
	v_lshl_add_u64 v[108:109], v[110:111], 0, v[108:109]

.LBB0_1161:
	s_waitcnt lgkmcnt(2)
	v_pk_add_f32 v[48:49], v[48:49], v[52:53]
	v_pk_add_f32 v[46:47], v[46:47], v[50:51]
	s_waitcnt lgkmcnt(0)
	v_pk_add_f32 v[40:41], v[40:41], v[44:45]
	v_pk_add_f32 v[38:39], v[38:39], v[42:43]
	v_pk_add_f32 v[40:41], v[48:49], v[40:41]
	v_pk_add_f32 v[38:39], v[46:47], v[38:39]
	s_nop 1
	v_add_f32_dpp v38, v38, v38 quad_perm:[1,0,3,2] row_mask:0xf bank_mask:0xf bound_ctrl:1
	v_add_f32_dpp v39, v39, v39 quad_perm:[1,0,3,2] row_mask:0xf bank_mask:0xf bound_ctrl:1
	v_add_f32_dpp v40, v40, v40 quad_perm:[1,0,3,2] row_mask:0xf bank_mask:0xf bound_ctrl:1
	v_add_f32_dpp v41, v41, v41 quad_perm:[1,0,3,2] row_mask:0xf bank_mask:0xf bound_ctrl:1
	v_add_f32_dpp v38, v38, v38 quad_perm:[2,3,0,1] row_mask:0xf bank_mask:0xf bound_ctrl:1
	v_add_f32_dpp v39, v39, v39 quad_perm:[2,3,0,1] row_mask:0xf bank_mask:0xf bound_ctrl:1
	v_add_f32_dpp v40, v40, v40 quad_perm:[2,3,0,1] row_mask:0xf bank_mask:0xf bound_ctrl:1
	v_add_f32_dpp v41, v41, v41 quad_perm:[2,3,0,1] row_mask:0xf bank_mask:0xf bound_ctrl:1
	v_cmp_eq_u32_e64 s[2:3], 1, v125
	s_nop 1
	v_cndmask_b32_e64 v38, v38, v39, s[2:3]
	v_cmp_eq_u32_e64 s[2:3], 2, v125
	s_nop 1
	v_cndmask_b32_e64 v38, v38, v40, s[2:3]
	v_cmp_eq_u32_e64 s[2:3], 3, v125
	s_nop 1
	v_cndmask_b32_e64 v40, v38, v41, s[2:3]
	global_store_dword v[108:109], v40, off
	v_lshl_add_u64 v[108:109], v[112:113], 0, v[108:109]

.LBB0_1221:
	s_waitcnt lgkmcnt(2)
	v_pk_add_f32 v[48:49], v[48:49], v[52:53]
	v_pk_add_f32 v[46:47], v[46:47], v[50:51]
	s_waitcnt lgkmcnt(0)
	v_pk_add_f32 v[40:41], v[40:41], v[44:45]
	v_pk_add_f32 v[38:39], v[38:39], v[42:43]
	v_pk_add_f32 v[40:41], v[48:49], v[40:41]
	v_pk_add_f32 v[38:39], v[46:47], v[38:39]
	s_nop 1
	v_add_f32_dpp v38, v38, v38 quad_perm:[1,0,3,2] row_mask:0xf bank_mask:0xf bound_ctrl:1
	v_add_f32_dpp v39, v39, v39 quad_perm:[1,0,3,2] row_mask:0xf bank_mask:0xf bound_ctrl:1
	v_add_f32_dpp v40, v40, v40 quad_perm:[1,0,3,2] row_mask:0xf bank_mask:0xf bound_ctrl:1
	v_add_f32_dpp v41, v41, v41 quad_perm:[1,0,3,2] row_mask:0xf bank_mask:0xf bound_ctrl:1
	v_add_f32_dpp v38, v38, v38 quad_perm:[2,3,0,1] row_mask:0xf bank_mask:0xf bound_ctrl:1
	v_add_f32_dpp v39, v39, v39 quad_perm:[2,3,0,1] row_mask:0xf bank_mask:0xf bound_ctrl:1
	v_add_f32_dpp v40, v40, v40 quad_perm:[2,3,0,1] row_mask:0xf bank_mask:0xf bound_ctrl:1
	v_add_f32_dpp v41, v41, v41 quad_perm:[2,3,0,1] row_mask:0xf bank_mask:0xf bound_ctrl:1
	s_andn2_b64 vcc, exec, s[60:61]
	v_cmp_eq_u32_e64 s[2:3], 1, v125
	s_nop 1
	v_cndmask_b32_e64 v38, v38, v39, s[2:3]
	v_cmp_eq_u32_e64 s[2:3], 2, v125
	s_nop 1
	v_cndmask_b32_e64 v38, v38, v40, s[2:3]
	v_cmp_eq_u32_e64 s[2:3], 3, v125
	s_nop 1
	v_cndmask_b32_e64 v40, v38, v41, s[2:3]
	global_store_dword v[108:109], v40, off
	v_lshl_add_u64 v[108:109], v[112:113], 0, v[108:109]
	s_waitcnt lgkmcnt(0)
	s_barrier
	s_cmpk_lt_u32 s49, 6
	s_cbranch_scc1 .Lscan_ld_drain_c
	s_cmpk_lt_u32 s49, 0x109
	s_cbranch_scc1 .Lscan_ld_steady_c

.LBB0_1277:
	s_waitcnt vmcnt(6)
	ds_read_b128 v[2:5], v0 offset:59392
	s_waitcnt vmcnt(4)
	ds_read_b128 v[6:9], v0 offset:59408
	s_waitcnt vmcnt(3)
	ds_read_b128 v[10:13], v0 offset:59424
	ds_read_b128 v[14:17], v0 offset:59440
	s_or_b32 s2, s24, 15
	v_add_u32_e32 v0, s24, v55
	s_waitcnt lgkmcnt(2)
	v_pk_add_f32 v[4:5], v[4:5], v[8:9]
	v_pk_add_f32 v[2:3], v[2:3], v[6:7]
	s_waitcnt lgkmcnt(0)
	v_pk_add_f32 v[6:7], v[12:13], v[16:17]
	v_pk_add_f32 v[8:9], v[10:11], v[14:15]
	v_add_u32_e32 v0, 0xff0, v0
	v_sub_u32_e32 v18, s2, v55
	v_pk_add_f32 v[4:5], v[4:5], v[6:7]
	v_pk_add_f32 v[2:3], v[2:3], v[8:9]
	v_cndmask_b32_e64 v18, v18, v0, s[16:17]
	s_nop 1
	v_add_f32_dpp v2, v2, v2 quad_perm:[1,0,3,2] row_mask:0xf bank_mask:0xf bound_ctrl:1
	v_add_f32_dpp v3, v3, v3 quad_perm:[1,0,3,2] row_mask:0xf bank_mask:0xf bound_ctrl:1
	v_add_f32_dpp v4, v4, v4 quad_perm:[1,0,3,2] row_mask:0xf bank_mask:0xf bound_ctrl:1
	v_add_f32_dpp v5, v5, v5 quad_perm:[1,0,3,2] row_mask:0xf bank_mask:0xf bound_ctrl:1
	v_add_f32_dpp v2, v2, v2 quad_perm:[2,3,0,1] row_mask:0xf bank_mask:0xf bound_ctrl:1
	v_add_f32_dpp v3, v3, v3 quad_perm:[2,3,0,1] row_mask:0xf bank_mask:0xf bound_ctrl:1
	v_add_f32_dpp v4, v4, v4 quad_perm:[2,3,0,1] row_mask:0xf bank_mask:0xf bound_ctrl:1
	v_add_f32_dpp v5, v5, v5 quad_perm:[2,3,0,1] row_mask:0xf bank_mask:0xf bound_ctrl:1
	v_cmp_eq_u32_e64 s[2:3], 1, v125
	s_nop 1
	v_cndmask_b32_e64 v6, v2, v3, s[2:3]
	v_cmp_eq_u32_e64 s[2:3], 2, v125
	s_nop 1
	v_cndmask_b32_e64 v6, v6, v4, s[2:3]
	v_cmp_eq_u32_e64 s[2:3], 3, v125
	s_nop 1
	v_cndmask_b32_e64 v6, v6, v5, s[2:3]
	v_ashrrev_i32_e32 v19, 31, v18
	v_readlane_b32 s2, v252, 14
	v_lshlrev_b64 v[2:3], 11, v[18:19]
	v_readlane_b32 s3, v252, 15
	s_mov_b32 s49, s21
	s_mov_b32 s51, s21
	v_lshl_add_u64 v[2:3], s[2:3], 0, v[2:3]
	v_lshl_add_u64 v[2:3], v[2:3], 0, s[20:21]
	v_lshl_add_u64 v[2:3], v[2:3], 0, s[48:49]
	v_lshl_add_u64 v[2:3], v[2:3], 0, s[50:51]
	v_lshlrev_b32_e32 v0, 2, v54
	v_lshl_add_u64 v[2:3], v[2:3], 0, v[0:1]
	global_store_dword v[108:109], v6, off
	s_mov_b32 s20, 0x10000
